# P2a solve: 16x16 blocked inverse - 16 substitution rounds for the diagonal blocks, blocks below the diagonal with f32 MFMA 16x16x4 (f32 accumulate), instead of 64 serial rounds
# speedup vs baseline: 1.0230x; 1.0114x over previous
; #define LAS __attribute__((address_space(3)))
; #define SOLVE_LD(i_) do { _Pragma("unroll") for (int a4 = 0; a4 < ((i_) + 15) / 16; ++a4) lq[(i_) % 3][a4] = *(const LAS f32x4*)(LP + (i_) * 64 + 4 * a4); } while (0)
; __device__ __forceinline__ void gdn_prep_phase(LAS unsigned char* lds, const GdnPrepArgs& A, int bid, int G, const unsigned char* zero_page) {
;     ...
;     if (!(pflg & 16)) {
;         const int dir = w >> 2, li = (w & 3) * 64 + lane, j = li >> 2, q = li & 3;
;         const LAS float* LP = (const LAS float*)(lds + (dir ? L_LPB : L_LPF)) + q * 16;
;         float t[16];
; #pragma unroll
;         for (int a = 0; a < 16; ++a) t[a] = 0.f;
;         f32x4 lq[3][4];
;     ...
;         SOLVE_LD(0); SOLVE_LD(1);
; #pragma unroll
;         for (int i = 0; i < 64; ++i) {
;             if (i + 2 < 48) SOLVE_LD(i + 2);
;             else if (i + 1 >= 48 && i + 1 < 64) SOLVE_LD(i + 1);
;             float p0 = 0.f, p1 = 0.f;
; #pragma unroll
;             for (int a4 = 0; a4 < (i + 15) / 16; ++a4) { const f32x4 lv = lq[i % 3][a4];
;                 p0 = __builtin_fmaf(lv.x, t[4 * a4], p0); p1 = __builtin_fmaf(lv.y, t[4 * a4 + 1], p1); p0 = __builtin_fmaf(lv.z, t[4 * a4 + 2], p0); p1 = __builtin_fmaf(lv.w, t[4 * a4 + 3], p1); }
;             float p = quad_sum(p0 + p1);
;             const float ti = (i == j ? 1.f : 0.f) - p;
;             if (q == (i & 3)) t[i >> 2] = ti;
.LBB0_197:
	s_and_b64 vcc, exec, s[2:3]
	s_cbranch_vccnz .LBB0_362
	s_lshl_b32 s67, s34, 4
	v_writelane_b32 v254, s42, 55
	s_lshl_b32 s3, s34, 3
	s_ashr_i32 s2, s67, 31
	v_writelane_b32 v254, s43, 56
	s_cmp_lt_i32 s34, 51
	v_writelane_b32 v254, s2, 57
	s_cselect_b64 s[4:5], -1, 0
	s_ashr_i32 s2, s38, 7
	s_bfe_u32 s6, s38, 0x10006
	v_writelane_b32 v254, s4, 59
	s_cmpk_gt_u32 s38, 0xff
	s_mov_b32 s7, 0x11000
	v_writelane_b32 v254, s5, 60
	s_cselect_b64 s[4:5], -1, 0
	s_cmpk_lt_u32 s38, 0x100
	s_mov_b32 s39, 0x15800
	s_cselect_b32 s7, s7, 0xcc00
	s_cselect_b32 s39, s39, 0x19800
	s_lshl_b32 s40, s2, 5
	v_and_b32_e32 v4, 31, v7
	s_add_i32 s7, s7, 0
	s_and_b32 s40, s40, 32
	v_or_b32_e32 v3, s40, v4
	v_mov_b32_e32 v6, s7
	s_movk_i32 s42, 0x110
	s_lshl_b32 s7, s6, 5
	v_lshrrev_b32_e32 v5, 5, v18
	v_mad_u32_u24 v11, v3, s42, v6
	v_or_b32_e32 v3, s7, v4
	v_lshlrev_b32_e32 v12, 4, v5
	v_lshl_or_b32 v15, v5, 2, s40
	v_lshlrev_b32_e32 v5, 1, v3
	s_add_i32 s40, 0, 0x1d800
	s_add_i32 s41, 0, 0x11000
	v_add_u32_e32 v8, s40, v5
	s_add_i32 s40, 0, 0x1fc00
	v_mov_b32_e32 v6, s41
	v_add_u32_e32 v9, s40, v5
	v_lshlrev_b32_e32 v5, 6, v7
	v_mad_u32_u24 v14, v3, s42, v6
	v_and_b32_e32 v5, 0xc0, v5
	s_add_i32 s40, 0, 0x15800
	v_bitop3_b32 v6, s7, 60, v4 bitop3:0xc8
	v_bitop3_b32 v4, s7, 63, v4 bitop3:0x36
	v_add3_u32 v13, s40, v5, v6
	v_lshlrev_b32_e32 v5, 4, v4
	v_lshrrev_b32_e32 v4, 2, v4
	v_and_b32_e32 v57, 15, v7
	v_and_or_b32 v16, v5, 48, v4
	v_lshl_or_b32 v4, s2, 4, v57
	s_movk_i32 s2, 0x90
	v_mul_lo_u32 v4, v4, s2
	s_lshl_b32 s2, s6, 6
	v_lshrrev_b32_e32 v6, 1, v7
	s_lshr_b32 s100, s38, 8
	s_and_b32 s38, s38, 0xc0
	s_mul_i32 s101, s100, 0xc0
	s_xor_b32 s101, s38, s101
	v_and_b32_e32 v58, 24, v6
	s_add_i32 s2, s2, 0
	v_add3_u32 v33, s2, v4, v58
	v_lshrrev_b32_e32 v4, 2, v7
	s_add_i32 s6, s38, 0
	v_lshlrev_b32_e32 v2, 1, v18
	v_or_b32_e32 v17, s101, v18
	s_lshr_b32 s101, s101, 6
	s_nop 0
	v_and_b32_e32 v59, 12, v4
	v_add_u32_e32 v62, s6, v58
	s_movk_i32 s6, 0x3fc
	v_readlane_b32 s42, v252, 62
	v_lshrrev_b32_e32 v32, 2, v17
	v_and_b32_e32 v249, 15, v32
	s_nop 0
	v_or_b32_e32 v4, s7, v59
	v_and_b32_e32 v60, 30, v2
	v_bitop3_b32 v2, v17, s6, v169 bitop3:0x6c
	v_mul_u32_u24_e32 v4, 0x110, v4
	v_add_u32_e32 v64, s42, v2
	v_lshlrev_b32_e32 v2, 1, v32
	v_add3_u32 v61, s41, v4, v60
	v_xor_b32_e32 v4, 0x7e, v2
	v_readlane_b32 s6, v252, 63
	s_or_b32 s52, s3, 7
	s_mulk_i32 s52, 0x300
	v_add_u32_e32 v34, s6, v4
	v_readlane_b32 s6, v254, 0
	s_or_b32 s53, s3, 1
	s_add_i32 s3, s52, 0xfffffd00
	v_add_u32_e32 v35, s6, v2
	v_cmp_gt_u32_e64 s[6:7], 2, v18
	v_and_b32_e32 v5, 3, v7
	s_add_i32 s39, s39, 0
	v_writelane_b32 v254, s6, 61
	v_and_b32_e32 v27, 64, v1
	v_lshl_add_u32 v56, v5, 6, s39
	v_writelane_b32 v254, s7, 62
	v_cmp_eq_u32_e64 s[6:7], 0, v18
	s_add_i32 s41, s41, s38
	v_bitop3_b32 v4, s38, v169, v18 bitop3:0xc8
	v_writelane_b32 v254, s6, 63
	v_xor_b32_e32 v21, 16, v1
	v_add_u32_e32 v27, 64, v27
	v_writelane_b32 v255, s7, 0
	v_writelane_b32 v255, s3, 1
	s_add_i32 s3, s52, 0xfffffa00
	v_writelane_b32 v255, s3, 3
	s_add_i32 s3, s52, 0xfffff700
	v_writelane_b32 v255, s3, 5
	s_add_i32 s3, s52, 0xfffff400
	v_writelane_b32 v255, s3, 7
	s_add_i32 s3, s52, 0xfffff100
	v_writelane_b32 v255, s3, 9
	s_add_i32 s3, s52, 0xffffee00
	v_writelane_b32 v255, s3, 11
	v_cmp_ge_u32_e64 s[38:39], v15, v3
	v_cmp_lt_i32_e32 vcc, v21, v27
	s_add_i32 s3, 0, 0x19800
	v_writelane_b32 v255, s38, 13
	v_cndmask_b32_e32 v21, v1, v21, vcc
	v_lshlrev_b32_e32 v69, 2, v21
	v_writelane_b32 v255, s39, 14
	v_cmp_gt_u32_e64 s[38:39], v15, v3
	v_xor_b32_e32 v21, 32, v1
	v_cmp_lt_i32_e32 vcc, v21, v27
	v_writelane_b32 v255, s38, 15
	v_lshlrev_b32_e32 v27, 6, v15
	v_add_u32_e32 v63, s41, v58
	v_writelane_b32 v255, s39, 16
	s_movk_i32 s38, 0xfc0
	v_bitop3_b32 v27, v16, s38, v27 bitop3:0x36
	v_lshl_add_u32 v73, v27, 2, s3
	v_or_b32_e32 v27, 1, v15
	v_lshl_add_u32 v74, v27, 2, s42
	v_cmp_lt_u32_e64 s[40:41], v27, v3
	v_lshlrev_b32_e32 v38, 8, v27
	v_lshlrev_b32_e32 v27, 6, v27
	v_cndmask_b32_e32 v21, v1, v21, vcc
	v_bitop3_b32 v27, v16, s38, v27 bitop3:0x36
	v_cmp_eq_u32_e32 vcc, 0, v249
	v_writelane_b32 v255, s40, 17
	v_lshl_add_u32 v75, v27, 2, s3
	v_or_b32_e32 v27, 2, v15
	v_cndmask_b32_e64 v104, 0, 1.0, vcc
	v_cmp_eq_u32_e32 vcc, 1, v249
	v_writelane_b32 v255, s41, 18
	v_cmp_lt_u32_e64 s[40:41], v27, v3
	v_cndmask_b32_e64 v105, 0, 1.0, vcc
	v_cmp_eq_u32_e32 vcc, 2, v249
	v_writelane_b32 v255, s40, 19
	v_lshl_add_u32 v76, v27, 2, s42
	v_cndmask_b32_e64 v106, 0, 1.0, vcc
	v_cmp_eq_u32_e32 vcc, 3, v249
	v_writelane_b32 v255, s41, 20
	v_cmp_gt_u32_e64 s[40:41], v27, v3
	v_lshlrev_b32_e32 v39, 8, v27
	v_lshlrev_b32_e32 v27, 6, v27
	v_cndmask_b32_e64 v107, 0, 1.0, vcc
	v_cmp_eq_u32_e32 vcc, 4, v249
	v_bitop3_b32 v27, v16, s38, v27 bitop3:0x36
	v_writelane_b32 v255, s40, 21
	v_cndmask_b32_e64 v109, 0, 1.0, vcc
	v_cmp_eq_u32_e32 vcc, 5, v249
	v_lshl_add_u32 v77, v27, 2, s3
	v_or_b32_e32 v27, 3, v15
	v_cndmask_b32_e64 v110, 0, 1.0, vcc
	v_cmp_eq_u32_e32 vcc, 6, v249
	v_writelane_b32 v255, s41, 22
	v_cmp_lt_u32_e64 s[40:41], v27, v3
	v_cndmask_b32_e64 v111, 0, 1.0, vcc
	v_cmp_eq_u32_e32 vcc, 7, v249
	v_writelane_b32 v255, s40, 23
	v_lshl_add_u32 v78, v27, 2, s42
	v_cndmask_b32_e64 v112, 0, 1.0, vcc
	v_cmp_eq_u32_e32 vcc, 8, v249
	v_writelane_b32 v255, s41, 24
	v_cmp_gt_u32_e64 s[40:41], v27, v3
	v_lshlrev_b32_e32 v40, 8, v27
	v_lshlrev_b32_e32 v27, 6, v27
	v_cndmask_b32_e64 v113, 0, 1.0, vcc
	v_cmp_eq_u32_e32 vcc, 9, v249
	v_bitop3_b32 v27, v16, s38, v27 bitop3:0x36
	v_writelane_b32 v255, s40, 25
	v_cndmask_b32_e64 v114, 0, 1.0, vcc
	v_cmp_eq_u32_e32 vcc, 10, v249
	v_lshl_add_u32 v79, v27, 2, s3
	v_or_b32_e32 v27, 8, v15
; #define LAS __attribute__((address_space(3)))
; #define SOLVE_LD(i_) do { _Pragma("unroll") for (int a4 = 0; a4 < ((i_) + 15) / 16; ++a4) lq[(i_) % 3][a4] = *(const LAS f32x4*)(LP + (i_) * 64 + 4 * a4); } while (0)
; __device__ __forceinline__ void gdn_prep_phase(LAS unsigned char* lds, const GdnPrepArgs& A, int bid, int G, const unsigned char* zero_page) {
;     ...
;     if (!(pflg & 16)) {
;         const int dir = w >> 2, li = (w & 3) * 64 + lane, j = li >> 2, q = li & 3;
;         const LAS float* LP = (const LAS float*)(lds + (dir ? L_LPB : L_LPF)) + q * 16;
;         float t[16];
; #pragma unroll
;         for (int a = 0; a < 16; ++a) t[a] = 0.f;
;         f32x4 lq[3][4];
;     ...
;         SOLVE_LD(0); SOLVE_LD(1);
; #pragma unroll
;         for (int i = 0; i < 64; ++i) {
;             if (i + 2 < 48) SOLVE_LD(i + 2);
;             else if (i + 1 >= 48 && i + 1 < 64) SOLVE_LD(i + 1);
;             float p0 = 0.f, p1 = 0.f;
; #pragma unroll
;             for (int a4 = 0; a4 < (i + 15) / 16; ++a4) { const f32x4 lv = lq[i % 3][a4];
;                 p0 = __builtin_fmaf(lv.x, t[4 * a4], p0); p1 = __builtin_fmaf(lv.y, t[4 * a4 + 1], p1); p0 = __builtin_fmaf(lv.z, t[4 * a4 + 2], p0); p1 = __builtin_fmaf(lv.w, t[4 * a4 + 3], p1); }
;             float p = quad_sum(p0 + p1);
;             const float ti = (i == j ? 1.f : 0.f) - p;
;             if (q == (i & 3)) t[i >> 2] = ti;
	v_cndmask_b32_e64 v115, 0, 1.0, vcc
	v_cmp_eq_u32_e32 vcc, 11, v249
	v_writelane_b32 v255, s41, 26
	v_cmp_lt_u32_e64 s[40:41], v27, v3
	v_cndmask_b32_e64 v116, 0, 1.0, vcc
	v_cmp_eq_u32_e32 vcc, 12, v249
	v_writelane_b32 v255, s40, 27
	v_lshl_add_u32 v80, v27, 2, s42
	v_cndmask_b32_e64 v118, 0, 1.0, vcc
	v_cmp_eq_u32_e32 vcc, 13, v249
	v_writelane_b32 v255, s41, 28
	v_cmp_gt_u32_e64 s[40:41], v27, v3
	v_lshlrev_b32_e32 v41, 8, v27
	v_lshlrev_b32_e32 v27, 6, v27
	v_cndmask_b32_e64 v119, 0, 1.0, vcc
	v_cmp_eq_u32_e32 vcc, 14, v249
	v_bitop3_b32 v27, v16, s38, v27 bitop3:0x36
	v_writelane_b32 v255, s40, 29
	v_cndmask_b32_e64 v120, 0, 1.0, vcc
	v_cmp_eq_u32_e32 vcc, 15, v249
	v_lshl_add_u32 v81, v27, 2, s3
	v_or_b32_e32 v27, 9, v15
	v_cndmask_b32_e64 v121, 0, 1.0, vcc
	v_cmp_eq_u32_e32 vcc, 16, v32
	v_writelane_b32 v255, s41, 30
	v_cmp_lt_u32_e64 s[40:41], v27, v3
	v_cndmask_b32_e64 v122, 0, 1.0, vcc
	v_cmp_eq_u32_e32 vcc, 17, v32
	v_writelane_b32 v255, s40, 31
	v_lshl_add_u32 v82, v27, 2, s42
	v_cndmask_b32_e64 v123, 0, 1.0, vcc
	v_cmp_eq_u32_e32 vcc, 18, v32
	v_writelane_b32 v255, s41, 32
	v_cmp_gt_u32_e64 s[40:41], v27, v3
	v_lshlrev_b32_e32 v42, 8, v27
	v_lshlrev_b32_e32 v27, 6, v27
	v_cndmask_b32_e64 v124, 0, 1.0, vcc
	v_cmp_eq_u32_e32 vcc, 19, v32
	v_bitop3_b32 v27, v16, s38, v27 bitop3:0x36
	v_writelane_b32 v255, s40, 33
	v_cndmask_b32_e64 v125, 0, 1.0, vcc
	v_cmp_eq_u32_e32 vcc, 20, v32
	v_lshl_add_u32 v83, v27, 2, s3
	v_or_b32_e32 v27, 10, v15
	v_cndmask_b32_e64 v126, 0, 1.0, vcc
	v_cmp_eq_u32_e32 vcc, 21, v32
	v_writelane_b32 v255, s41, 34
	v_cmp_lt_u32_e64 s[40:41], v27, v3
	v_cndmask_b32_e64 v127, 0, 1.0, vcc
	v_cmp_eq_u32_e32 vcc, 22, v32
	v_writelane_b32 v255, s40, 35
	v_lshl_add_u32 v84, v27, 2, s42
	v_cndmask_b32_e64 v128, 0, 1.0, vcc
	v_cmp_eq_u32_e32 vcc, 23, v32
	v_writelane_b32 v255, s41, 36
	v_cmp_gt_u32_e64 s[40:41], v27, v3
	v_lshlrev_b32_e32 v43, 8, v27
	v_lshlrev_b32_e32 v27, 6, v27
	v_cndmask_b32_e64 v129, 0, 1.0, vcc
	v_cmp_eq_u32_e32 vcc, 24, v32
	v_bitop3_b32 v27, v16, s38, v27 bitop3:0x36
	v_writelane_b32 v255, s40, 37
	v_cndmask_b32_e64 v136, 0, 1.0, vcc
	v_cmp_eq_u32_e32 vcc, 25, v32
	v_lshl_add_u32 v85, v27, 2, s3
	v_or_b32_e32 v27, 11, v15
	v_cndmask_b32_e64 v137, 0, 1.0, vcc
	v_cmp_eq_u32_e32 vcc, 26, v32
	v_writelane_b32 v255, s41, 38
	v_cmp_lt_u32_e64 s[40:41], v27, v3
	v_cndmask_b32_e64 v138, 0, 1.0, vcc
	v_cmp_eq_u32_e32 vcc, 27, v32
	v_writelane_b32 v255, s40, 39
	v_lshl_add_u32 v86, v27, 2, s42
	v_cndmask_b32_e64 v139, 0, 1.0, vcc
	v_cmp_eq_u32_e32 vcc, 28, v32
	v_writelane_b32 v255, s41, 40
	v_cmp_gt_u32_e64 s[40:41], v27, v3
	v_lshlrev_b32_e32 v44, 8, v27
	v_lshlrev_b32_e32 v27, 6, v27
	v_cndmask_b32_e64 v140, 0, 1.0, vcc
	v_cmp_eq_u32_e32 vcc, 29, v32
	v_bitop3_b32 v27, v16, s38, v27 bitop3:0x36
	v_writelane_b32 v255, s40, 41
	v_cndmask_b32_e64 v141, 0, 1.0, vcc
	v_cmp_eq_u32_e32 vcc, 30, v32
	v_lshl_add_u32 v87, v27, 2, s3
	v_or_b32_e32 v27, 16, v15
	v_cndmask_b32_e64 v142, 0, 1.0, vcc
	v_cmp_eq_u32_e32 vcc, 31, v32
	v_writelane_b32 v255, s41, 42
	v_cmp_lt_u32_e64 s[40:41], v27, v3
	v_cndmask_b32_e64 v143, 0, 1.0, vcc
	v_cmp_eq_u32_e32 vcc, 32, v32
	v_writelane_b32 v255, s40, 43
	v_lshl_add_u32 v88, v27, 2, s42
	v_cndmask_b32_e64 v144, 0, 1.0, vcc
	v_cmp_eq_u32_e32 vcc, 33, v32
	v_writelane_b32 v255, s41, 44
	v_cmp_gt_u32_e64 s[40:41], v27, v3
	v_lshlrev_b32_e32 v45, 8, v27
	v_lshlrev_b32_e32 v27, 6, v27
	v_cndmask_b32_e64 v145, 0, 1.0, vcc
	v_cmp_eq_u32_e32 vcc, 34, v32
	v_bitop3_b32 v27, v16, s38, v27 bitop3:0x36
	v_or_b32_e32 v46, 17, v15
	v_cndmask_b32_e64 v146, 0, 1.0, vcc
	v_cmp_eq_u32_e32 vcc, 35, v32
	v_lshl_add_u32 v89, v27, 2, s3
	v_lshlrev_b32_e32 v27, 6, v46
	v_cndmask_b32_e64 v147, 0, 1.0, vcc
	v_cmp_eq_u32_e32 vcc, 36, v32
	v_bitop3_b32 v27, v16, s38, v27 bitop3:0x36
	v_or_b32_e32 v48, 18, v15
	v_cndmask_b32_e64 v148, 0, 1.0, vcc
	v_cmp_eq_u32_e32 vcc, 37, v32
	v_lshl_add_u32 v91, v27, 2, s3
	v_lshlrev_b32_e32 v27, 6, v48
	v_cndmask_b32_e64 v149, 0, 1.0, vcc
	v_cmp_eq_u32_e32 vcc, 38, v32
	v_bitop3_b32 v27, v16, s38, v27 bitop3:0x36
	v_or_b32_e32 v230, 19, v15
	v_cndmask_b32_e64 v150, 0, 1.0, vcc
	v_cmp_eq_u32_e32 vcc, 39, v32
	v_lshl_add_u32 v93, v27, 2, s3
	v_lshlrev_b32_e32 v27, 6, v230
	v_cndmask_b32_e64 v151, 0, 1.0, vcc
	v_cmp_eq_u32_e32 vcc, 40, v32
	v_bitop3_b32 v27, v16, s38, v27 bitop3:0x36
	v_or_b32_e32 v231, 24, v15
	v_cndmask_b32_e64 v152, 0, 1.0, vcc
	v_cmp_eq_u32_e32 vcc, 41, v32
	v_lshl_add_u32 v95, v27, 2, s3
	v_lshlrev_b32_e32 v27, 6, v231
	v_cndmask_b32_e64 v153, 0, 1.0, vcc
	v_cmp_eq_u32_e32 vcc, 42, v32
	v_bitop3_b32 v27, v16, s38, v27 bitop3:0x36
	v_or_b32_e32 v232, 25, v15
	v_cndmask_b32_e64 v154, 0, 1.0, vcc
	v_cmp_eq_u32_e32 vcc, 43, v32
	v_lshl_add_u32 v97, v27, 2, s3
	v_lshlrev_b32_e32 v27, 6, v232
	v_cndmask_b32_e64 v155, 0, 1.0, vcc
	v_cmp_eq_u32_e32 vcc, 44, v32
	v_bitop3_b32 v27, v16, s38, v27 bitop3:0x36
	v_or_b32_e32 v233, 26, v15
	v_cndmask_b32_e64 v156, 0, 1.0, vcc
	v_cmp_eq_u32_e32 vcc, 45, v32
	v_lshl_add_u32 v99, v27, 2, s3
	v_lshlrev_b32_e32 v27, 6, v233
	v_cndmask_b32_e64 v157, 0, 1.0, vcc
	v_cmp_eq_u32_e32 vcc, 46, v32
	v_lshl_add_u32 v72, v15, 2, s42
	v_cmp_lt_u32_e64 s[6:7], v15, v3
	v_mul_u32_u24_e32 v36, 0x90, v15
	v_lshlrev_b32_e32 v37, 8, v15
	v_bitop3_b32 v27, v16, s38, v27 bitop3:0x36
	v_or_b32_e32 v15, 27, v15
	v_cndmask_b32_e64 v158, 0, 1.0, vcc
	v_cmp_eq_u32_e32 vcc, 47, v32
	v_lshl_add_u32 v101, v27, 2, s3
	v_lshlrev_b32_e32 v27, 6, v15
	v_cndmask_b32_e64 v159, 0, 1.0, vcc
	v_cmp_eq_u32_e32 vcc, 48, v32
	v_bitop3_b32 v26, v7, 63, 3 bitop3:0x6c
	v_bitop3_b32 v16, v16, s38, v27 bitop3:0x36
	v_cndmask_b32_e64 v160, 0, 1.0, vcc
; #define LAS __attribute__((address_space(3)))
; __device__ __forceinline__ void gdn_prep_phase(LAS unsigned char* lds, const GdnPrepArgs& A, int bid, int G, const unsigned char* zero_page) {
;     ...
;     if (!(pflg & 16)) {
;         const int dir = w >> 2, li = (w & 3) * 64 + lane, j = li >> 2, q = li & 3;
;         const LAS float* LP = (const LAS float*)(lds + (dir ? L_LPB : L_LPF)) + q * 16;
;         float t[16];
; #pragma unroll
;         for (int a = 0; a < 16; ++a) t[a] = 0.f;
;         f32x4 lq[3][4];
;     ...
;         SOLVE_LD(0); SOLVE_LD(1);
; #pragma unroll
;         for (int i = 0; i < 64; ++i) {
;             if (i + 2 < 48) SOLVE_LD(i + 2);
;             else if (i + 1 >= 48 && i + 1 < 64) SOLVE_LD(i + 1);
;             float p0 = 0.f, p1 = 0.f;
; #pragma unroll
;             for (int a4 = 0; a4 < (i + 15) / 16; ++a4) { const f32x4 lv = lq[i % 3][a4];
;                 p0 = __builtin_fmaf(lv.x, t[4 * a4], p0); p1 = __builtin_fmaf(lv.y, t[4 * a4 + 1], p1); p0 = __builtin_fmaf(lv.z, t[4 * a4 + 2], p0); p1 = __builtin_fmaf(lv.w, t[4 * a4 + 3], p1); }
;             float p = quad_sum(p0 + p1);
;             const float ti = (i == j ? 1.f : 0.f) - p;
;             if (q == (i & 3)) t[i >> 2] = ti;
;             if ((i & 7) == 3 && !(pflg & 64)) {
;                 constexpr int kk = 0; const int k8 = i >> 3, b = w + 8 * (k8 & 1); v4u f; int off; (void)kk;
;                 if (k8 < 2)      { f = frag16_rm(lds + L_KN, QS_, b >> 2, b & 3, lane); off = B_KA + b * 1024; }
;                 else if (k8 < 4) { f = frag16_rm(lds + L_QN, QS_, b >> 2, b & 3, lane); off = B_QA + b * 1024; }
;                 else if (k8 < 6) { f = frag16_tr(lds + L_KN, QS_, b >> 1, b & 1, lane); off = B_KT + b * 1024; }
;                 else             { f = frag16_rm(lds + (k8 == 6 ? L_AF : L_AB), AS_, w >> 1, w & 1, lane); off = (k8 == 6 ? B_AF : B_AB) + w * 1024; }
;                 *(v4u*)(blob + off + lane * 16) = f; }
;             __builtin_amdgcn_sched_barrier(0);
;         }
;     ...
;         const LAS float* sc = (const LAS float*)(lds + L_SC);
;         if (dir == 0) { const float bj = sc[128 + j];
; #pragma unroll
;             for (int a = 0; a < 16; ++a) *(LAS unsigned short*)(lds + L_TBF + (4 * a + q) * AS_ + j * 2) = (unsigned short)(pkbf(t[a] * bj, 0.f) & 0xffffu);
;         } else { const int jo = 63 - j; const float bj = sc[192 + jo];
; #pragma unroll
	v_cmp_eq_u32_e32 vcc, 49, v32
	v_lshl_add_u32 v103, v16, 2, s3
	v_mul_u32_u24_e32 v16, 0x90, v26
	v_bitop3_b32 v26, v7, 55, 3 bitop3:0x6c
	v_cndmask_b32_e64 v161, 0, 1.0, vcc
	v_cmp_eq_u32_e32 vcc, 50, v32
	v_mul_u32_u24_e32 v210, 0x90, v26
	v_bitop3_b32 v26, v7, 51, 3 bitop3:0x6c
	v_cndmask_b32_e64 v162, 0, 1.0, vcc
	v_cmp_eq_u32_e32 vcc, 51, v32
	v_mul_u32_u24_e32 v211, 0x90, v26
	v_bitop3_b32 v26, v7, 47, 3 bitop3:0x6c
	v_cndmask_b32_e64 v163, 0, 1.0, vcc
	v_cmp_eq_u32_e32 vcc, 52, v32
	v_mul_u32_u24_e32 v212, 0x90, v26
	v_bitop3_b32 v26, v7, 43, 3 bitop3:0x6c
	v_readlane_b32 s38, v251, 39
	v_cndmask_b32_e64 v173, 0, 1.0, vcc
	v_cmp_eq_u32_e32 vcc, 53, v32
	v_add_u32_e32 v54, 0, v130
	v_mul_u32_u24_e32 v213, 0x90, v26
	v_bitop3_b32 v26, v7, 39, 3 bitop3:0x6c
	v_lshlrev_b32_e32 v130, 3, v18
	v_readlane_b32 s39, v251, 40
	v_cndmask_b32_e64 v174, 0, 1.0, vcc
	v_cmp_eq_u32_e32 vcc, 54, v32
	v_writelane_b32 v255, s40, 45
	v_mul_u32_u24_e32 v214, 0x90, v26
	v_bitop3_b32 v26, v7, 35, 3 bitop3:0x6c
	v_lshl_add_u64 v[28:29], s[38:39], 0, v[130:131]
	v_readlane_b32 s38, v251, 41
	v_cndmask_b32_e64 v175, 0, 1.0, vcc
	v_cmp_eq_u32_e32 vcc, 55, v32
	v_writelane_b32 v255, s41, 46
	v_mul_u32_u24_e32 v215, 0x90, v26
	v_bitop3_b32 v26, v7, 31, 3 bitop3:0x6c
	v_readlane_b32 s39, v251, 42
	s_add_i32 s41, s34, 8
	v_cndmask_b32_e64 v176, 0, 1.0, vcc
	v_cmp_eq_u32_e32 vcc, 56, v32
	v_mul_u32_u24_e32 v216, 0x90, v26
	v_bitop3_b32 v26, v7, 27, 3 bitop3:0x6c
	v_lshl_add_u64 v[30:31], s[38:39], 0, v[130:131]
	s_lshl_b32 s38, s41, 2
	v_cndmask_b32_e64 v177, 0, 1.0, vcc
	v_cmp_eq_u32_e32 vcc, 57, v32
	v_mul_u32_u24_e32 v217, 0x90, v26
	v_bitop3_b32 v26, v7, 23, 3 bitop3:0x6c
	v_readlane_b32 s68, v250, 10
	s_and_b32 s38, s38, 0xffffff0
	v_cndmask_b32_e64 v178, 0, 1.0, vcc
	v_cmp_eq_u32_e32 vcc, 58, v32
	v_mul_u32_u24_e32 v218, 0x90, v26
	v_bitop3_b32 v26, v7, 19, 3 bitop3:0x6c
	v_readlane_b32 s72, v250, 14
	s_lshl_b32 s40, s34, 2
	v_or_b32_e32 v117, s38, v57
	s_lshl_b32 s38, s41, 10
	v_cndmask_b32_e64 v179, 0, 1.0, vcc
	v_cmp_eq_u32_e32 vcc, 59, v32
	s_lshl_b32 s41, s41, 4
	s_lshl_b32 s2, s34, 10
	v_mul_u32_u24_e32 v219, 0x90, v26
	v_bitop3_b32 v26, v7, 15, 3 bitop3:0x6c
	s_and_b32 s3, s40, 0xffffff0
	v_cndmask_b32_e64 v180, 0, 1.0, vcc
	v_cmp_eq_u32_e32 vcc, 60, v32
	s_and_b32 s72, s41, 0xffffffe0
	s_add_i32 s41, s34, -8
	v_mul_u32_u24_e32 v220, 0x90, v26
	v_bitop3_b32 v26, v7, 11, 3 bitop3:0x6c
	v_or_b32_e32 v108, s3, v57
	s_ashr_i32 s3, s2, 31
	v_cndmask_b32_e64 v181, 0, 1.0, vcc
	v_cmp_eq_u32_e32 vcc, 61, v32
	v_writelane_b32 v255, s41, 47
	v_lshrrev_b32_e32 v10, 4, v18
	v_bitop3_b32 v17, v7, 59, 3 bitop3:0x6c
	v_mul_u32_u24_e32 v221, 0x90, v26
	v_bitop3_b32 v26, v7, 7, 3 bitop3:0x6c
	v_bitop3_b32 v7, v7, 3, v7 bitop3:0xc
	v_readlane_b32 s70, v250, 12
	v_cndmask_b32_e64 v182, 0, 1.0, vcc
	v_cmp_eq_u32_e32 vcc, 62, v32
	v_writelane_b32 v255, s2, 48
	v_lshlrev_b32_e32 v22, 4, v18
	v_add_u32_e32 v65, s42, v4
	v_or_b32_e32 v2, 64, v18
	v_or_b32_e32 v4, 0x80, v18
	v_or_b32_e32 v6, 0xc0, v18
	v_lshlrev_b32_e32 v47, 8, v46
	v_lshlrev_b32_e32 v49, 8, v48
	v_lshlrev_b32_e32 v203, 8, v230
	v_lshlrev_b32_e32 v204, 8, v231
	v_lshlrev_b32_e32 v205, 8, v232
	v_lshlrev_b32_e32 v206, 8, v233
	v_lshlrev_b32_e32 v207, 8, v15
	v_mul_u32_u24_e32 v17, 0x90, v17
	v_mul_u32_u24_e32 v222, 0x90, v26
	v_mul_u32_u24_e32 v7, 0x90, v7
	v_mul_u32_u24_e32 v224, 0x90, v5
	v_readlane_b32 s69, v250, 11
	v_readlane_b32 s71, v250, 13
	v_readlane_b32 s74, v250, 16
	v_readlane_b32 s75, v250, 17
	v_readlane_b32 s76, v250, 18
	v_readlane_b32 s77, v250, 19
	v_readlane_b32 s78, v250, 20
	v_readlane_b32 s79, v250, 21
	v_readlane_b32 s80, v250, 22
	v_readlane_b32 s81, v250, 23
	s_movk_i32 s70, 0x110
	v_cndmask_b32_e64 v183, 0, 1.0, vcc
	v_cmp_eq_u32_e32 vcc, 63, v32
	v_or_b32_e32 v189, s40, v10
	v_writelane_b32 v255, s3, 49
	s_add_i32 s40, s2, 0
	v_lshlrev_b32_e32 v20, 8, v18
	v_and_b32_e32 v24, 0xf0, v22
	v_mov_b32_e32 v25, v131
	v_lshl_add_u32 v55, v3, 2, s42
	v_mov_b32_e32 v23, v131
	v_lshl_add_u32 v66, v2, 2, s42
	v_lshl_add_u32 v67, v4, 2, s42
	v_lshl_add_u32 v68, v6, 2, s42
	v_lshlrev_b32_e32 v70, 2, v21
	s_mulk_i32 s53, 0x110
	v_add_u32_e32 v71, 0x11000, v54
	v_mov_b32_e32 v21, v131
	v_lshl_add_u32 v90, v46, 2, s42
	v_lshl_add_u32 v92, v48, 2, s42
	v_lshl_add_u32 v94, v230, 2, s42
	v_lshl_add_u32 v96, v231, 2, s42
	v_lshl_add_u32 v98, v232, 2, s42
	v_lshl_add_u32 v100, v233, 2, s42
	v_lshl_add_u32 v102, v15, 2, s42
	v_lshl_add_u64 v[26:27], s[74:75], 0, v[130:131]
	v_mul_lo_u32 v108, v108, s70
	v_mul_lo_u32 v117, v117, s70
	s_ashr_i32 s39, s38, 31
	v_cndmask_b32_e64 v184, 0, 1.0, vcc
	s_and_b32 s71, s67, 0xffffffe0
	v_add_u32_e32 v185, 0x1d800, v33
	v_add_u32_e32 v186, 0x1d820, v33
	v_add_u32_e32 v187, 0x1fc00, v33
	v_add_u32_e32 v188, 0x1fc20, v33
	v_writelane_b32 v255, s40, 50
	v_add_u32_e32 v190, v11, v12
	v_add_u32_e32 v191, v14, v12
	v_add_u32_e32 v192, v13, v37
	v_add_u32_e32 v193, v13, v38
	v_add_u32_e32 v194, v13, v39
	v_add_u32_e32 v195, v13, v40
	v_add_u32_e32 v196, v13, v41
	v_add_u32_e32 v197, v13, v42
	v_add_u32_e32 v198, v13, v43
	v_add_u32_e32 v199, v13, v44
	v_add_u32_e32 v200, v13, v45
	v_add_u32_e32 v201, v13, v47
	v_add_u32_e32 v202, v13, v49
	v_add_u32_e32 v203, v13, v203
	v_add_u32_e32 v204, v13, v204
	v_add_u32_e32 v205, v13, v205
	v_add_u32_e32 v206, v13, v206
	v_add_u32_e32 v207, v13, v207
	v_add_u32_e32 v208, v34, v16
	v_add_u32_e32 v209, v34, v17
	v_add_u32_e32 v210, v34, v210
	v_add_u32_e32 v211, v34, v211
	v_add_u32_e32 v212, v34, v212
	v_add_u32_e32 v213, v34, v213
	v_add_u32_e32 v214, v34, v214
	v_add_u32_e32 v215, v34, v215
	v_add_u32_e32 v216, v34, v216
	v_add_u32_e32 v217, v34, v217
	v_add_u32_e32 v218, v34, v218
	v_add_u32_e32 v219, v34, v219
	v_add_u32_e32 v220, v34, v220
	v_add_u32_e32 v221, v34, v221
	v_add_u32_e32 v222, v34, v222
	v_add_u32_e32 v223, v34, v7
	v_add_u32_e32 v224, v35, v224
	v_lshlrev_b32_e32 v225, 2, v2
	v_lshlrev_b32_e32 v226, 2, v4
	v_lshlrev_b32_e32 v227, 2, v6
	v_add_u32_e32 v228, v8, v36
	v_add_u32_e32 v229, v9, v36
	s_mov_b32 s56, s85
	v_cmp_lt_u32_e64 s[74:75], v46, v3
	v_cmp_gt_u32_e64 s[76:77], v46, v3
	v_cmp_lt_u32_e64 s[58:59], v48, v3
	v_cmp_gt_u32_e64 s[60:61], v48, v3
	v_cmp_lt_u32_e64 s[62:63], v230, v3
	v_cmp_gt_u32_e64 s[64:65], v230, v3
	v_cmp_lt_u32_e64 s[84:85], v231, v3
	v_cmp_gt_u32_e64 s[78:79], v231, v3
	v_cmp_lt_u32_e64 s[80:81], v232, v3
	v_cmp_gt_u32_e64 s[26:27], v232, v3
	v_cmp_lt_u32_e64 s[28:29], v233, v3
	v_cmp_gt_u32_e64 s[30:31], v233, v3
	v_cmp_lt_u32_e64 s[24:25], v15, v3
	v_cmp_gt_u32_e64 s[36:37], v15, v3
	v_cmp_eq_u32_e64 s[86:87], 0, v5
	v_cmp_eq_u32_e64 s[88:89], 1, v5
	v_cmp_eq_u32_e64 s[90:91], 2, v5
	v_cmp_eq_u32_e64 s[92:93], 3, v5
	s_mov_b32 s68, 0x55555556
	s_movk_i32 s69, 0x800
	v_readlane_b32 s73, v250, 15
	v_readlane_b32 s82, v250, 24
	v_readlane_b32 s83, v250, 25
	s_waitcnt vmcnt(0)
	s_nop 0
	s_branch .LBB0_201

; #define LAS __attribute__((address_space(3)))
; #define SOLVE_LD(i_) do { _Pragma("unroll") for (int a4 = 0; a4 < ((i_) + 15) / 16; ++a4) lq[(i_) % 3][a4] = *(const LAS f32x4*)(LP + (i_) * 64 + 4 * a4); } while (0)
; __device__ __forceinline__ void gdn_prep_phase(LAS unsigned char* lds, const GdnPrepArgs& A, int bid, int G, const unsigned char* zero_page) {
;     ...
;     if (!(pflg & 16)) {
;         const int dir = w >> 2, li = (w & 3) * 64 + lane, j = li >> 2, q = li & 3;
;         const LAS float* LP = (const LAS float*)(lds + (dir ? L_LPB : L_LPF)) + q * 16;
;         float t[16];
; #pragma unroll
;         for (int a = 0; a < 16; ++a) t[a] = 0.f;
;         f32x4 lq[3][4];
;     ...
;         SOLVE_LD(0); SOLVE_LD(1);
; #pragma unroll
;         for (int i = 0; i < 64; ++i) {
;             if (i + 2 < 48) SOLVE_LD(i + 2);
;             else if (i + 1 >= 48 && i + 1 < 64) SOLVE_LD(i + 1);
;             float p0 = 0.f, p1 = 0.f;
; #pragma unroll
;             for (int a4 = 0; a4 < (i + 15) / 16; ++a4) { const f32x4 lv = lq[i % 3][a4];
;                 p0 = __builtin_fmaf(lv.x, t[4 * a4], p0); p1 = __builtin_fmaf(lv.y, t[4 * a4 + 1], p1); p0 = __builtin_fmaf(lv.z, t[4 * a4 + 2], p0); p1 = __builtin_fmaf(lv.w, t[4 * a4 + 3], p1); }
;             float p = quad_sum(p0 + p1);
;             const float ti = (i == j ? 1.f : 0.f) - p;
;             if (q == (i & 3)) t[i >> 2] = ti;
.LBB0_337:
	s_waitcnt lgkmcnt(0)
	s_barrier
	s_nop 0
	s_mul_i32 s46, s101, 0x1010
	s_mul_i32 s47, s100, 0x2400
	s_add_i32 s47, s47, 0x22000
	s_lshl_b32 s48, s101, 11
	s_lshl_b32 s49, s100, 14
	s_add_i32 s49, s49, 0x15800
	s_lshl_b32 s50, s100, 1
	s_sub_i32 s50, 1, s50
	s_mul_i32 s51, s100, 0x47ee
	s_add_i32 s51, s51, 0x22000
	s_mul_i32 s54, s100, 508
	s_add_i32 s54, s54, 0x15600
	s_lshl_b32 s55, s101, 4
	s_add_i32 s1, s47, s48
	s_add_i32 s32, s1, 0x400
	s_add_i32 s2, s49, s46
	s_add_i32 s2, s2, 0x1000
	s_mul_i32 s3, s50, 0x240
	s_mul_i32 s57, s50, 0x90
	v_mbcnt_lo_u32_b32 v2, -1, 0
	v_mbcnt_hi_u32_b32 v2, -1, v2
	v_and_b32_e32 v3, 3, v2
	v_lshrrev_b32_e32 v4, 2, v2
	v_add_u32_e32 v173, s46, v56
	v_lshlrev_b32_e32 v236, 2, v3
	v_lshl_or_b32 v236, v4, 6, v236
	v_add_u32_e32 v174, s1, v236
	v_lshlrev_b32_e32 v236, 2, v4
	v_lshl_or_b32 v236, v3, 6, v236
	v_add_u32_e32 v175, s32, v236
	v_and_b32_e32 v237, 15, v2
	v_lshrrev_b32_e32 v249, 4, v2
	v_lshlrev_b32_e32 v236, 2, v249
	v_lshl_or_b32 v236, v237, 8, v236
	v_add_u32_e32 v176, s2, v236
	v_add_u32_e32 v177, 0x1000, v176
	v_add_u32_e32 v178, 0x1000, v177
	v_lshlrev_b32_e32 v236, 4, v249
	v_lshl_or_b32 v236, v237, 6, v236
	v_add_u32_e32 v180, s1, v236
	v_add_u32_e32 v179, 0x400, v180
	v_add_u32_e32 v236, s55, v4
	v_lshlrev_b32_e32 v130, 1, v236
	v_mul_u32_u24_e32 v3, 0x90, v3
	v_add_u32_e32 v130, v130, v3
	v_mul_lo_u32 v130, v130, s50
	v_add_u32_e32 v181, s51, v130
	v_lshlrev_b32_e32 v236, 2, v236
	v_mul_lo_u32 v236, v236, s50
	v_add_u32_e32 v244, s54, v236
	v_mov_b32_e32 v182, s3
	v_mov_b32_e32 v184, s57
	v_lshl_add_u32 v236, v249, 2, s55
	v_mul_u32_u24_e32 v236, 0x90, v236
	v_add_u32_e32 v130, s55, v237
	v_lshl_add_u32 v236, v130, 1, v236
	v_mul_lo_u32 v236, v236, s50
	v_add_u32_e32 v183, s51, v236
	v_lshlrev_b32_e32 v130, 2, v130
	v_mul_lo_u32 v130, v130, s50
	v_add_u32_e32 v245, s54, v130
	ds_read_b128 v[32:35], v173 offset:256
	ds_read_b128 v[36:39], v173 offset:512
	ds_read_b128 v[40:43], v173 offset:768
	ds_read_b128 v[44:47], v173 offset:1024
	ds_read_b128 v[6:9], v173 offset:1280
	ds_read_b128 v[10:13], v173 offset:1536
	ds_read_b128 v[14:17], v173 offset:1792
	ds_read_b128 v[238:241], v173 offset:2048
	ds_read_b128 v[136:139], v173 offset:2304
	ds_read_b128 v[140:143], v173 offset:2560
	ds_read_b128 v[144:147], v173 offset:2816
	ds_read_b128 v[148:151], v173 offset:3072
	ds_read_b128 v[152:155], v173 offset:3328
	ds_read_b128 v[156:159], v173 offset:3584
	ds_read_b128 v[160:163], v173 offset:3840
	v_mov_b32_e32 v233, 0
	v_mov_b32_e32 v234, 0
	v_mov_b32_e32 v235, 0
	v_cndmask_b32_e64 v232, 0, v104, s[86:87]
	s_waitcnt lgkmcnt(14)
	v_pk_fma_f32 v[32:33], v[32:33], v[232:233], 0 op_sel_hi:[1,1,0]
	s_nop 0
	v_add_f32_e32 v32, v32, v33
	s_nop 1
	v_add_f32_dpp v32, v32, v32 quad_perm:[1,0,3,2] row_mask:0xf bank_mask:0xf bound_ctrl:1
	s_nop 1
	v_add_f32_dpp v32, v32, v32 quad_perm:[2,3,0,1] row_mask:0xf bank_mask:0xf bound_ctrl:1
	v_sub_f32_e32 v32, v105, v32
	v_cndmask_b32_e64 v232, v232, v32, s[88:89]
	s_waitcnt lgkmcnt(13)
	v_pk_fma_f32 v[36:37], v[36:37], v[232:233], 0 op_sel_hi:[1,1,0]
	s_nop 0
	v_add_f32_e32 v36, v36, v37
	s_nop 1
	v_add_f32_dpp v36, v36, v36 quad_perm:[1,0,3,2] row_mask:0xf bank_mask:0xf bound_ctrl:1
	s_nop 1
	v_add_f32_dpp v36, v36, v36 quad_perm:[2,3,0,1] row_mask:0xf bank_mask:0xf bound_ctrl:1
	v_sub_f32_e32 v36, v106, v36
	v_cndmask_b32_e64 v232, v232, v36, s[90:91]
	s_waitcnt lgkmcnt(12)
	v_pk_fma_f32 v[40:41], v[40:41], v[232:233], 0 op_sel_hi:[1,1,0]
	s_nop 0
	v_add_f32_e32 v40, v40, v41
	s_nop 1
	v_add_f32_dpp v40, v40, v40 quad_perm:[1,0,3,2] row_mask:0xf bank_mask:0xf bound_ctrl:1
	s_nop 1
	v_add_f32_dpp v40, v40, v40 quad_perm:[2,3,0,1] row_mask:0xf bank_mask:0xf bound_ctrl:1
	v_sub_f32_e32 v40, v107, v40
	v_cndmask_b32_e64 v232, v232, v40, s[92:93]
	s_waitcnt lgkmcnt(11)
	v_pk_fma_f32 v[44:45], v[44:45], v[232:233], 0 op_sel_hi:[1,1,0]
	s_nop 0
	v_add_f32_e32 v44, v44, v45
	s_nop 1
	v_add_f32_dpp v44, v44, v44 quad_perm:[1,0,3,2] row_mask:0xf bank_mask:0xf bound_ctrl:1
	s_nop 1
	v_add_f32_dpp v44, v44, v44 quad_perm:[2,3,0,1] row_mask:0xf bank_mask:0xf bound_ctrl:1
	v_sub_f32_e32 v44, v109, v44
	v_cndmask_b32_e64 v233, v233, v44, s[86:87]
	s_waitcnt lgkmcnt(10)
	v_pk_fma_f32 v[6:7], v[6:7], v[232:233], 0 op_sel_hi:[1,1,0]
	s_nop 0
	v_add_f32_e32 v6, v6, v7
	s_nop 1
	v_add_f32_dpp v6, v6, v6 quad_perm:[1,0,3,2] row_mask:0xf bank_mask:0xf bound_ctrl:1
	s_nop 1
	v_add_f32_dpp v6, v6, v6 quad_perm:[2,3,0,1] row_mask:0xf bank_mask:0xf bound_ctrl:1
	v_sub_f32_e32 v6, v110, v6
	v_cndmask_b32_e64 v233, v233, v6, s[88:89]
	s_waitcnt lgkmcnt(9)
	v_pk_fma_f32 v[10:11], v[10:11], v[232:233], 0 op_sel_hi:[1,1,0]
	s_nop 0
	v_add_f32_e32 v10, v10, v11
	s_nop 1
	v_add_f32_dpp v10, v10, v10 quad_perm:[1,0,3,2] row_mask:0xf bank_mask:0xf bound_ctrl:1
	s_nop 1
	v_add_f32_dpp v10, v10, v10 quad_perm:[2,3,0,1] row_mask:0xf bank_mask:0xf bound_ctrl:1
	v_sub_f32_e32 v10, v111, v10
	v_cndmask_b32_e64 v233, v233, v10, s[90:91]
	s_waitcnt lgkmcnt(8)
	v_pk_fma_f32 v[14:15], v[14:15], v[232:233], 0 op_sel_hi:[1,1,0]
	s_nop 0
	v_add_f32_e32 v14, v14, v15
	s_nop 1
	v_add_f32_dpp v14, v14, v14 quad_perm:[1,0,3,2] row_mask:0xf bank_mask:0xf bound_ctrl:1
	s_nop 1
	v_add_f32_dpp v14, v14, v14 quad_perm:[2,3,0,1] row_mask:0xf bank_mask:0xf bound_ctrl:1
	v_sub_f32_e32 v14, v112, v14
	v_cndmask_b32_e64 v233, v233, v14, s[92:93]
	s_waitcnt lgkmcnt(7)
	v_pk_fma_f32 v[238:239], v[238:239], v[232:233], 0 op_sel_hi:[1,1,0]
	s_nop 0
	v_add_f32_e32 v238, v238, v239
	s_nop 1
	v_add_f32_dpp v238, v238, v238 quad_perm:[1,0,3,2] row_mask:0xf bank_mask:0xf bound_ctrl:1
	s_nop 1
	v_add_f32_dpp v238, v238, v238 quad_perm:[2,3,0,1] row_mask:0xf bank_mask:0xf bound_ctrl:1
	v_sub_f32_e32 v238, v113, v238
	v_cndmask_b32_e64 v234, v234, v238, s[86:87]
	s_waitcnt lgkmcnt(6)
; #define SOLVE_LD(i_) do { _Pragma("unroll") for (int a4 = 0; a4 < ((i_) + 15) / 16; ++a4) lq[(i_) % 3][a4] = *(const LAS f32x4*)(LP + (i_) * 64 + 4 * a4); } while (0)
; __device__ __forceinline__ void gdn_prep_phase(LAS unsigned char* lds, const GdnPrepArgs& A, int bid, int G, const unsigned char* zero_page) {
;     ...
;         for (int i = 0; i < 64; ++i) {
;             if (i + 2 < 48) SOLVE_LD(i + 2);
;             else if (i + 1 >= 48 && i + 1 < 64) SOLVE_LD(i + 1);
;             float p0 = 0.f, p1 = 0.f;
; #pragma unroll
;             for (int a4 = 0; a4 < (i + 15) / 16; ++a4) { const f32x4 lv = lq[i % 3][a4];
;                 p0 = __builtin_fmaf(lv.x, t[4 * a4], p0); p1 = __builtin_fmaf(lv.y, t[4 * a4 + 1], p1); p0 = __builtin_fmaf(lv.z, t[4 * a4 + 2], p0); p1 = __builtin_fmaf(lv.w, t[4 * a4 + 3], p1); }
;             float p = quad_sum(p0 + p1);
;             const float ti = (i == j ? 1.f : 0.f) - p;
;             if (q == (i & 3)) t[i >> 2] = ti;
	v_pk_fma_f32 v[136:137], v[136:137], v[232:233], 0 op_sel_hi:[1,1,0]
	s_nop 0
	v_pk_fma_f32 v[136:137], v[138:139], v[234:235], v[136:137]
	s_nop 0
	v_add_f32_e32 v136, v136, v137
	s_nop 1
	v_add_f32_dpp v136, v136, v136 quad_perm:[1,0,3,2] row_mask:0xf bank_mask:0xf bound_ctrl:1
	s_nop 1
	v_add_f32_dpp v136, v136, v136 quad_perm:[2,3,0,1] row_mask:0xf bank_mask:0xf bound_ctrl:1
	v_sub_f32_e32 v136, v114, v136
	v_cndmask_b32_e64 v234, v234, v136, s[88:89]
	s_waitcnt lgkmcnt(5)
	v_pk_fma_f32 v[140:141], v[140:141], v[232:233], 0 op_sel_hi:[1,1,0]
	s_nop 0
	v_pk_fma_f32 v[140:141], v[142:143], v[234:235], v[140:141]
	s_nop 0
	v_add_f32_e32 v140, v140, v141
	s_nop 1
	v_add_f32_dpp v140, v140, v140 quad_perm:[1,0,3,2] row_mask:0xf bank_mask:0xf bound_ctrl:1
	s_nop 1
	v_add_f32_dpp v140, v140, v140 quad_perm:[2,3,0,1] row_mask:0xf bank_mask:0xf bound_ctrl:1
	v_sub_f32_e32 v140, v115, v140
	v_cndmask_b32_e64 v234, v234, v140, s[90:91]
	s_waitcnt lgkmcnt(4)
	v_pk_fma_f32 v[144:145], v[144:145], v[232:233], 0 op_sel_hi:[1,1,0]
	s_nop 0
	v_pk_fma_f32 v[144:145], v[146:147], v[234:235], v[144:145]
	s_nop 0
	v_add_f32_e32 v144, v144, v145
	s_nop 1
	v_add_f32_dpp v144, v144, v144 quad_perm:[1,0,3,2] row_mask:0xf bank_mask:0xf bound_ctrl:1
	s_nop 1
	v_add_f32_dpp v144, v144, v144 quad_perm:[2,3,0,1] row_mask:0xf bank_mask:0xf bound_ctrl:1
	v_sub_f32_e32 v144, v116, v144
	v_cndmask_b32_e64 v234, v234, v144, s[92:93]
	s_waitcnt lgkmcnt(3)
	v_pk_fma_f32 v[148:149], v[148:149], v[232:233], 0 op_sel_hi:[1,1,0]
	s_nop 0
	v_pk_fma_f32 v[148:149], v[150:151], v[234:235], v[148:149]
	s_nop 0
	v_add_f32_e32 v148, v148, v149
	s_nop 1
	v_add_f32_dpp v148, v148, v148 quad_perm:[1,0,3,2] row_mask:0xf bank_mask:0xf bound_ctrl:1
	s_nop 1
	v_add_f32_dpp v148, v148, v148 quad_perm:[2,3,0,1] row_mask:0xf bank_mask:0xf bound_ctrl:1
	v_sub_f32_e32 v148, v118, v148
	v_cndmask_b32_e64 v235, v235, v148, s[86:87]
	s_waitcnt lgkmcnt(2)
	v_pk_fma_f32 v[152:153], v[152:153], v[232:233], 0 op_sel_hi:[1,1,0]
	s_nop 0
	v_pk_fma_f32 v[152:153], v[154:155], v[234:235], v[152:153]
	s_nop 0
	v_add_f32_e32 v152, v152, v153
	s_nop 1
	v_add_f32_dpp v152, v152, v152 quad_perm:[1,0,3,2] row_mask:0xf bank_mask:0xf bound_ctrl:1
	s_nop 1
	v_add_f32_dpp v152, v152, v152 quad_perm:[2,3,0,1] row_mask:0xf bank_mask:0xf bound_ctrl:1
	v_sub_f32_e32 v152, v119, v152
	v_cndmask_b32_e64 v235, v235, v152, s[88:89]
	s_waitcnt lgkmcnt(1)
	v_pk_fma_f32 v[156:157], v[156:157], v[232:233], 0 op_sel_hi:[1,1,0]
	s_nop 0
	v_pk_fma_f32 v[156:157], v[158:159], v[234:235], v[156:157]
	s_nop 0
	v_add_f32_e32 v156, v156, v157
	s_nop 1
	v_add_f32_dpp v156, v156, v156 quad_perm:[1,0,3,2] row_mask:0xf bank_mask:0xf bound_ctrl:1
	s_nop 1
	v_add_f32_dpp v156, v156, v156 quad_perm:[2,3,0,1] row_mask:0xf bank_mask:0xf bound_ctrl:1
	v_sub_f32_e32 v156, v120, v156
	v_cndmask_b32_e64 v235, v235, v156, s[90:91]
	s_waitcnt lgkmcnt(0)
	v_pk_fma_f32 v[160:161], v[160:161], v[232:233], 0 op_sel_hi:[1,1,0]
	s_nop 0
	v_pk_fma_f32 v[160:161], v[162:163], v[234:235], v[160:161]
	s_nop 0
	v_add_f32_e32 v160, v160, v161
	s_nop 1
	v_add_f32_dpp v160, v160, v160 quad_perm:[1,0,3,2] row_mask:0xf bank_mask:0xf bound_ctrl:1
	s_nop 1
	v_add_f32_dpp v160, v160, v160 quad_perm:[2,3,0,1] row_mask:0xf bank_mask:0xf bound_ctrl:1
	v_sub_f32_e32 v160, v121, v160
	v_cndmask_b32_e64 v235, v235, v160, s[92:93]
	ds_write_b32 v174, v232
	ds_write_b32 v174, v233 offset:16
	ds_write_b32 v174, v234 offset:32
	ds_write_b32 v174, v235 offset:48
	v_xor_b32_e32 v6, 0x80000000, v232
	v_xor_b32_e32 v7, 0x80000000, v233
	v_xor_b32_e32 v8, 0x80000000, v234
	v_xor_b32_e32 v9, 0x80000000, v235
	ds_write_b32 v175, v6
	ds_write_b32 v175, v7 offset:256
	ds_write_b32 v175, v8 offset:512
	ds_write_b32 v175, v9 offset:768
	s_waitcnt lgkmcnt(0)
	s_barrier
	ds_read_b128 v[136:139], v180
	s_cmp_gt_u32 s101, 2
	s_cbranch_scc1 .Ls4b_end
	ds_read2_b32 v[144:145], v176 offset0:0 offset1:16
	ds_read2_b32 v[146:147], v176 offset0:32 offset1:48
	ds_read_b128 v[140:143], v179 offset:2048
	s_waitcnt lgkmcnt(2)
	v_mfma_f32_16x16x4_f32 v[156:159], v144, v136, 0
	v_mfma_f32_16x16x4_f32 v[156:159], v145, v137, v[156:159]
	s_waitcnt lgkmcnt(1)
	v_mfma_f32_16x16x4_f32 v[156:159], v146, v138, v[156:159]
	v_mfma_f32_16x16x4_f32 v[156:159], v147, v139, v[156:159]
	s_waitcnt lgkmcnt(0)
	s_nop 8
	v_mfma_f32_16x16x4_f32 v[160:163], v140, v156, 0
	v_mfma_f32_16x16x4_f32 v[160:163], v141, v157, v[160:163]
	v_mfma_f32_16x16x4_f32 v[160:163], v142, v158, v[160:163]
	v_mfma_f32_16x16x4_f32 v[160:163], v143, v159, v[160:163]
	s_cmp_gt_u32 s101, 1
	s_cbranch_scc1 .Ls4b_end
	ds_read2_b32 v[144:145], v177 offset0:0 offset1:16
	ds_read2_b32 v[146:147], v177 offset0:32 offset1:48
	ds_read2_b32 v[148:149], v177 offset0:4 offset1:20
	ds_read2_b32 v[150:151], v177 offset0:36 offset1:52
	ds_read_b128 v[140:143], v179 offset:4096
	s_waitcnt lgkmcnt(4)
	v_mfma_f32_16x16x4_f32 v[156:159], v144, v136, 0
	v_mfma_f32_16x16x4_f32 v[156:159], v145, v137, v[156:159]
	s_waitcnt lgkmcnt(3)
	v_mfma_f32_16x16x4_f32 v[156:159], v146, v138, v[156:159]
	v_mfma_f32_16x16x4_f32 v[156:159], v147, v139, v[156:159]
	s_waitcnt lgkmcnt(2)
	v_mfma_f32_16x16x4_f32 v[156:159], v148, v160, v[156:159]
	v_mfma_f32_16x16x4_f32 v[156:159], v149, v161, v[156:159]
	s_waitcnt lgkmcnt(1)
	v_mfma_f32_16x16x4_f32 v[156:159], v150, v162, v[156:159]
	v_mfma_f32_16x16x4_f32 v[156:159], v151, v163, v[156:159]
	s_waitcnt lgkmcnt(0)
	s_nop 8
	v_mfma_f32_16x16x4_f32 v[122:125], v140, v156, 0
	v_mfma_f32_16x16x4_f32 v[122:125], v141, v157, v[122:125]
	v_mfma_f32_16x16x4_f32 v[122:125], v142, v158, v[122:125]
	v_mfma_f32_16x16x4_f32 v[122:125], v143, v159, v[122:125]
	s_cmp_gt_u32 s101, 0
	s_cbranch_scc1 .Ls4b_end
; #define LAS __attribute__((address_space(3)))
; #define SOLVE_LD(i_) do { _Pragma("unroll") for (int a4 = 0; a4 < ((i_) + 15) / 16; ++a4) lq[(i_) % 3][a4] = *(const LAS f32x4*)(LP + (i_) * 64 + 4 * a4); } while (0)
; __device__ __forceinline__ void gdn_prep_phase(LAS unsigned char* lds, const GdnPrepArgs& A, int bid, int G, const unsigned char* zero_page) {
;     ...
;     if (!(pflg & 16)) {
;         const int dir = w >> 2, li = (w & 3) * 64 + lane, j = li >> 2, q = li & 3;
;         const LAS float* LP = (const LAS float*)(lds + (dir ? L_LPB : L_LPF)) + q * 16;
;         float t[16];
; #pragma unroll
;         for (int a = 0; a < 16; ++a) t[a] = 0.f;
;         f32x4 lq[3][4];
;     ...
;         SOLVE_LD(0); SOLVE_LD(1);
; #pragma unroll
;         for (int i = 0; i < 64; ++i) {
;             if (i + 2 < 48) SOLVE_LD(i + 2);
;             else if (i + 1 >= 48 && i + 1 < 64) SOLVE_LD(i + 1);
;             float p0 = 0.f, p1 = 0.f;
; #pragma unroll
;             for (int a4 = 0; a4 < (i + 15) / 16; ++a4) { const f32x4 lv = lq[i % 3][a4];
;                 p0 = __builtin_fmaf(lv.x, t[4 * a4], p0); p1 = __builtin_fmaf(lv.y, t[4 * a4 + 1], p1); p0 = __builtin_fmaf(lv.z, t[4 * a4 + 2], p0); p1 = __builtin_fmaf(lv.w, t[4 * a4 + 3], p1); }
;             float p = quad_sum(p0 + p1);
;             const float ti = (i == j ? 1.f : 0.f) - p;
;             if (q == (i & 3)) t[i >> 2] = ti;
;             if ((i & 7) == 3 && !(pflg & 64)) {
;                 constexpr int kk = 0; const int k8 = i >> 3, b = w + 8 * (k8 & 1); v4u f; int off; (void)kk;
;                 if (k8 < 2)      { f = frag16_rm(lds + L_KN, QS_, b >> 2, b & 3, lane); off = B_KA + b * 1024; }
;                 else if (k8 < 4) { f = frag16_rm(lds + L_QN, QS_, b >> 2, b & 3, lane); off = B_QA + b * 1024; }
;                 else if (k8 < 6) { f = frag16_tr(lds + L_KN, QS_, b >> 1, b & 1, lane); off = B_KT + b * 1024; }
;                 else             { f = frag16_rm(lds + (k8 == 6 ? L_AF : L_AB), AS_, w >> 1, w & 1, lane); off = (k8 == 6 ? B_AF : B_AB) + w * 1024; }
;                 *(v4u*)(blob + off + lane * 16) = f; }
	ds_read2_b32 v[144:145], v178 offset0:0 offset1:16
	ds_read2_b32 v[146:147], v178 offset0:32 offset1:48
	ds_read2_b32 v[148:149], v178 offset0:4 offset1:20
	ds_read2_b32 v[150:151], v178 offset0:36 offset1:52
	ds_read2_b32 v[152:153], v178 offset0:8 offset1:24
	ds_read2_b32 v[154:155], v178 offset0:40 offset1:56
	ds_read_b128 v[140:143], v179 offset:6144
	s_waitcnt lgkmcnt(6)
	v_mfma_f32_16x16x4_f32 v[156:159], v144, v136, 0
	v_mfma_f32_16x16x4_f32 v[156:159], v145, v137, v[156:159]
	s_waitcnt lgkmcnt(5)
	v_mfma_f32_16x16x4_f32 v[156:159], v146, v138, v[156:159]
	v_mfma_f32_16x16x4_f32 v[156:159], v147, v139, v[156:159]
	s_waitcnt lgkmcnt(4)
	v_mfma_f32_16x16x4_f32 v[156:159], v148, v160, v[156:159]
	v_mfma_f32_16x16x4_f32 v[156:159], v149, v161, v[156:159]
	s_waitcnt lgkmcnt(3)
	v_mfma_f32_16x16x4_f32 v[156:159], v150, v162, v[156:159]
	v_mfma_f32_16x16x4_f32 v[156:159], v151, v163, v[156:159]
	s_waitcnt lgkmcnt(2)
	v_mfma_f32_16x16x4_f32 v[156:159], v152, v122, v[156:159]
	v_mfma_f32_16x16x4_f32 v[156:159], v153, v123, v[156:159]
	s_waitcnt lgkmcnt(1)
	v_mfma_f32_16x16x4_f32 v[156:159], v154, v124, v[156:159]
	v_mfma_f32_16x16x4_f32 v[156:159], v155, v125, v[156:159]
	s_waitcnt lgkmcnt(0)
	s_nop 8
	v_mfma_f32_16x16x4_f32 v[126:129], v140, v156, 0
	v_mfma_f32_16x16x4_f32 v[126:129], v141, v157, v[126:129]
	v_mfma_f32_16x16x4_f32 v[126:129], v142, v158, v[126:129]
	v_mfma_f32_16x16x4_f32 v[126:129], v143, v159, v[126:129]
.Ls4b_end:
	s_waitcnt lgkmcnt(0)
	v_lshl_add_u64 v[6:7], s[40:41], 0, v[22:23]
	v_readlane_b32 s2, v255, 48
	v_add_u32_e32 v9, v63, v108
	ds_read2_b64 v[10:13], v9 offset1:4
	v_readlane_b32 s3, v255, 49
	s_nop 1
	v_lshl_add_u64 v[8:9], v[6:7], 0, s[2:3]
	s_waitcnt lgkmcnt(0)
	global_store_dwordx4 v[8:9], v[10:13], off
	v_add_u32_e32 v14, v63, v117
	ds_read2_b64 v[14:17], v14 offset1:4
	v_lshl_add_u64 v[32:33], v[6:7], 0, s[38:39]
	s_waitcnt lgkmcnt(0)
	global_store_dwordx4 v[32:33], v[14:17], off
	s_movk_i32 s40, 0x4000
	v_add_co_u32_e32 v12, vcc, s40, v8
	s_nop 1
	v_addc_co_u32_e32 v13, vcc, 0, v9, vcc
	v_add_u32_e32 v11, v62, v108
	v_add_u32_e32 v11, 0xc800, v11
	ds_read2_b64 v[34:37], v11 offset0:128 offset1:132
	s_waitcnt lgkmcnt(0)
	global_store_dwordx4 v[12:13], v[34:37], off
	v_add_co_u32_e32 v230, vcc, s40, v32
	s_nop 1
	v_addc_co_u32_e32 v231, vcc, 0, v33, vcc
	v_add_u32_e32 v13, v62, v117
	v_add_u32_e32 v13, 0xc800, v13
	ds_read2_b64 v[42:45], v13 offset0:128 offset1:132
	s_waitcnt lgkmcnt(0)
	global_store_dwordx4 v[230:231], v[42:45], off
	s_mov_b32 s40, 0x8000
	v_add_u32_e32 v15, s71, v61
	ds_read_u16 v16, v15 offset:816
	ds_read_u16 v17, v15 offset:4352
	ds_read_u16 v239, v15 offset:4624
	ds_read_u16 v240, v15 offset:4896
	ds_read_u16 v241, v15 offset:5168
	ds_read_u16 v242, v15
	ds_read_u16 v243, v15 offset:272
	ds_read_u16 v15, v15 offset:544
	s_waitcnt lgkmcnt(3)
	v_perm_b32 v241, v241, v240, s33
	v_perm_b32 v240, v239, v17, s33
	s_waitcnt lgkmcnt(0)
	v_perm_b32 v239, v16, v15, s33
	v_add_co_u32_e32 v16, vcc, s40, v8
	v_perm_b32 v238, v243, v242, s33
	s_nop 0
	v_addc_co_u32_e32 v17, vcc, 0, v9, vcc
	global_store_dwordx4 v[16:17], v[238:241], off offset:2048
	v_add_u32_e32 v38, s72, v61
	v_add_co_u32_e32 v32, vcc, s40, v32
	s_nop 1
	v_addc_co_u32_e32 v33, vcc, 0, v33, vcc
	ds_read_u16 v39, v38 offset:816
	ds_read_u16 v40, v38 offset:4352
	ds_read_u16 v46, v38 offset:4624
	ds_read_u16 v41, v38 offset:4896
	ds_read_u16 v47, v38 offset:5168
	ds_read_u16 v48, v38
	ds_read_u16 v49, v38 offset:272
	ds_read_u16 v38, v38 offset:544
	s_waitcnt lgkmcnt(3)
	v_perm_b32 v41, v47, v41, s33
	v_perm_b32 v40, v46, v40, s33
	s_waitcnt lgkmcnt(0)
	v_perm_b32 v39, v39, v38, s33
	v_perm_b32 v38, v49, v48, s33
	global_store_dwordx4 v[32:33], v[38:41], off offset:2048
	s_mov_b32 s40, 0xe000
	v_add_co_u32_e32 v46, vcc, s40, v8
	s_nop 1
	v_addc_co_u32_e32 v47, vcc, 0, v9, vcc
	ds_read_b64 v[42:43], v185
	ds_read_b64 v[44:45], v186
	s_waitcnt lgkmcnt(0)
	global_store_dwordx4 v[46:47], v[42:45], off offset:2048
	s_mov_b32 s40, 0x12000
	v_add_co_u32_e32 v8, vcc, s40, v8
	s_nop 1
	v_addc_co_u32_e32 v9, vcc, 0, v9, vcc
	ds_read_b64 v[40:41], v187
	ds_read_b64 v[42:43], v188
	s_waitcnt lgkmcnt(0)
	global_store_dwordx4 v[8:9], v[40:43], off offset:2048
	s_waitcnt lgkmcnt(0)
	s_barrier
	ds_read_b32 v246, v244
	ds_read_b32 v248, v245
	v_mov_b32_e32 v2, 0
	s_cmp_eq_u32 s101, 3
	s_cbranch_scc1 .Ls4o3
	s_cmp_eq_u32 s101, 2
	s_cbranch_scc1 .Ls4o2
	s_cmp_eq_u32 s101, 1
	s_cbranch_scc1 .Ls4o1
	s_waitcnt lgkmcnt(1)
	v_mul_f32_e32 v3, v232, v246
	v_cvt_pk_bf16_f32 v3, v3, s0
	ds_write_b16 v181, v3
	v_add_u32_e32 v181, v182, v181
	v_mul_f32_e32 v3, v233, v246
	v_cvt_pk_bf16_f32 v3, v3, s0
	ds_write_b16 v181, v3
	v_add_u32_e32 v181, v182, v181
	v_mul_f32_e32 v3, v234, v246
	v_cvt_pk_bf16_f32 v3, v3, s0
	ds_write_b16 v181, v3
	v_add_u32_e32 v181, v182, v181
	v_mul_f32_e32 v3, v235, v246
	v_cvt_pk_bf16_f32 v3, v3, s0
	ds_write_b16 v181, v3
	v_lshl_add_u32 v183, v184, 4, v183
	v_mov_b32_e32 v4, v183
	s_waitcnt lgkmcnt(4)
	v_mul_f32_e32 v3, v160, v248
	v_cvt_pk_bf16_f32 v3, v3, s0
	ds_write_b16 v4, v3
	v_add_u32_e32 v4, v184, v4
	v_mul_f32_e32 v3, v161, v248
	v_cvt_pk_bf16_f32 v3, v3, s0
	ds_write_b16 v4, v3
	v_add_u32_e32 v4, v184, v4
	v_mul_f32_e32 v3, v162, v248
	v_cvt_pk_bf16_f32 v3, v3, s0
	ds_write_b16 v4, v3
	v_add_u32_e32 v4, v184, v4
	v_mul_f32_e32 v3, v163, v248
	v_cvt_pk_bf16_f32 v3, v3, s0
	ds_write_b16 v4, v3
	v_lshl_add_u32 v183, v184, 4, v183
	v_mov_b32_e32 v4, v183
	v_mul_f32_e32 v3, v122, v248
	v_cvt_pk_bf16_f32 v3, v3, s0
	ds_write_b16 v4, v3
	v_add_u32_e32 v4, v184, v4
	v_mul_f32_e32 v3, v123, v248
	v_cvt_pk_bf16_f32 v3, v3, s0
	ds_write_b16 v4, v3
	v_add_u32_e32 v4, v184, v4
	v_mul_f32_e32 v3, v124, v248
	v_cvt_pk_bf16_f32 v3, v3, s0
	ds_write_b16 v4, v3
	v_add_u32_e32 v4, v184, v4
	v_mul_f32_e32 v3, v125, v248
	v_cvt_pk_bf16_f32 v3, v3, s0
	ds_write_b16 v4, v3
	v_lshl_add_u32 v183, v184, 4, v183
	v_mov_b32_e32 v4, v183
	v_mul_f32_e32 v3, v126, v248
	v_cvt_pk_bf16_f32 v3, v3, s0
	ds_write_b16 v4, v3
	v_add_u32_e32 v4, v184, v4
	v_mul_f32_e32 v3, v127, v248
	v_cvt_pk_bf16_f32 v3, v3, s0
	ds_write_b16 v4, v3
	v_add_u32_e32 v4, v184, v4
	v_mul_f32_e32 v3, v128, v248
	v_cvt_pk_bf16_f32 v3, v3, s0
	ds_write_b16 v4, v3
	v_add_u32_e32 v4, v184, v4
	v_mul_f32_e32 v3, v129, v248
	v_cvt_pk_bf16_f32 v3, v3, s0
	ds_write_b16 v4, v3
	s_branch .Ls4o_end
; #define LAS __attribute__((address_space(3)))
; __device__ __forceinline__ unsigned pkbf(float a, float b) { bf16x2_t v = __builtin_convertvector((f32x2_t){a, b}, bf16x2_t); return __builtin_bit_cast(unsigned, v); }
; #define LBAR() do { asm volatile("s_waitcnt lgkmcnt(0)" ::: "memory"); __builtin_amdgcn_s_barrier(); asm volatile("" ::: "memory"); } while (0)
; __device__ __forceinline__ void gdn_prep_phase(LAS unsigned char* lds, const GdnPrepArgs& A, int bid, int G, const unsigned char* zero_page) {
;     ...
;         const LAS float* sc = (const LAS float*)(lds + L_SC);
;         if (dir == 0) { const float bj = sc[128 + j];
; #pragma unroll
;             for (int a = 0; a < 16; ++a) *(LAS unsigned short*)(lds + L_TBF + (4 * a + q) * AS_ + j * 2) = (unsigned short)(pkbf(t[a] * bj, 0.f) & 0xffffu);
;         } else { const int jo = 63 - j; const float bj = sc[192 + jo];
; #pragma unroll
;             for (int a = 0; a < 16; ++a) *(LAS unsigned short*)(lds + L_TBB + (63 - (4 * a + q)) * AS_ + jo * 2) = (unsigned short)(pkbf(t[a] * bj, 0.f) & 0xffffu);
;         }
;     }
;     LBAR();
;     const bool has_next = unit + G < nunits;
;     if (has_next && w == 0) gdn_prep_s1(lds, A, unit + G, smn, lane, pflg);
;     if (!(pflg & 64) && !(has_next && w == 0)) for (int l = has_next ? w - 1 : w; l < 16; l += has_next ? 7 : 8)
;         gdn_prep_block(lds, blob, l < 8 ? 48 + l : 56 + l, lane, pflg);
.Ls4o1:
	s_waitcnt lgkmcnt(0)
	ds_write_b16 v181, v2
	v_add_u32_e32 v181, v182, v181
	ds_write_b16 v181, v2
	v_add_u32_e32 v181, v182, v181
	ds_write_b16 v181, v2
	v_add_u32_e32 v181, v182, v181
	ds_write_b16 v181, v2
	v_add_u32_e32 v181, v182, v181
	v_mul_f32_e32 v3, v232, v246
	v_cvt_pk_bf16_f32 v3, v3, s0
	ds_write_b16 v181, v3
	v_add_u32_e32 v181, v182, v181
	v_mul_f32_e32 v3, v233, v246
	v_cvt_pk_bf16_f32 v3, v3, s0
	ds_write_b16 v181, v3
	v_add_u32_e32 v181, v182, v181
	v_mul_f32_e32 v3, v234, v246
	v_cvt_pk_bf16_f32 v3, v3, s0
	ds_write_b16 v181, v3
	v_add_u32_e32 v181, v182, v181
	v_mul_f32_e32 v3, v235, v246
	v_cvt_pk_bf16_f32 v3, v3, s0
	ds_write_b16 v181, v3
	v_lshl_add_u32 v183, v184, 4, v183
	v_mov_b32_e32 v4, v183
	v_mul_f32_e32 v3, v160, v248
	v_cvt_pk_bf16_f32 v3, v3, s0
	ds_write_b16 v4, v3
	v_add_u32_e32 v4, v184, v4
	v_mul_f32_e32 v3, v161, v248
	v_cvt_pk_bf16_f32 v3, v3, s0
	ds_write_b16 v4, v3
	v_add_u32_e32 v4, v184, v4
	v_mul_f32_e32 v3, v162, v248
	v_cvt_pk_bf16_f32 v3, v3, s0
	ds_write_b16 v4, v3
	v_add_u32_e32 v4, v184, v4
	v_mul_f32_e32 v3, v163, v248
	v_cvt_pk_bf16_f32 v3, v3, s0
	ds_write_b16 v4, v3
	v_lshl_add_u32 v183, v184, 4, v183
	v_mov_b32_e32 v4, v183
	v_mul_f32_e32 v3, v122, v248
	v_cvt_pk_bf16_f32 v3, v3, s0
	ds_write_b16 v4, v3
	v_add_u32_e32 v4, v184, v4
	v_mul_f32_e32 v3, v123, v248
	v_cvt_pk_bf16_f32 v3, v3, s0
	ds_write_b16 v4, v3
	v_add_u32_e32 v4, v184, v4
	v_mul_f32_e32 v3, v124, v248
	v_cvt_pk_bf16_f32 v3, v3, s0
	ds_write_b16 v4, v3
	v_add_u32_e32 v4, v184, v4
	v_mul_f32_e32 v3, v125, v248
	v_cvt_pk_bf16_f32 v3, v3, s0
	ds_write_b16 v4, v3
	s_branch .Ls4o_end
.Ls4o2:
	s_waitcnt lgkmcnt(0)
	ds_write_b16 v181, v2
	v_add_u32_e32 v181, v182, v181
	ds_write_b16 v181, v2
	v_add_u32_e32 v181, v182, v181
	ds_write_b16 v181, v2
	v_add_u32_e32 v181, v182, v181
	ds_write_b16 v181, v2
	v_add_u32_e32 v181, v182, v181
	ds_write_b16 v181, v2
	v_add_u32_e32 v181, v182, v181
	ds_write_b16 v181, v2
	v_add_u32_e32 v181, v182, v181
	ds_write_b16 v181, v2
	v_add_u32_e32 v181, v182, v181
	ds_write_b16 v181, v2
	v_add_u32_e32 v181, v182, v181
	v_mul_f32_e32 v3, v232, v246
	v_cvt_pk_bf16_f32 v3, v3, s0
	ds_write_b16 v181, v3
	v_add_u32_e32 v181, v182, v181
	v_mul_f32_e32 v3, v233, v246
	v_cvt_pk_bf16_f32 v3, v3, s0
	ds_write_b16 v181, v3
	v_add_u32_e32 v181, v182, v181
	v_mul_f32_e32 v3, v234, v246
	v_cvt_pk_bf16_f32 v3, v3, s0
	ds_write_b16 v181, v3
	v_add_u32_e32 v181, v182, v181
	v_mul_f32_e32 v3, v235, v246
	v_cvt_pk_bf16_f32 v3, v3, s0
	ds_write_b16 v181, v3
	v_lshl_add_u32 v183, v184, 4, v183
	v_mov_b32_e32 v4, v183
	v_mul_f32_e32 v3, v160, v248
	v_cvt_pk_bf16_f32 v3, v3, s0
	ds_write_b16 v4, v3
	v_add_u32_e32 v4, v184, v4
	v_mul_f32_e32 v3, v161, v248
	v_cvt_pk_bf16_f32 v3, v3, s0
	ds_write_b16 v4, v3
	v_add_u32_e32 v4, v184, v4
	v_mul_f32_e32 v3, v162, v248
	v_cvt_pk_bf16_f32 v3, v3, s0
	ds_write_b16 v4, v3
	v_add_u32_e32 v4, v184, v4
	v_mul_f32_e32 v3, v163, v248
	v_cvt_pk_bf16_f32 v3, v3, s0
	ds_write_b16 v4, v3
	s_branch .Ls4o_end
.Ls4o3:
	s_waitcnt lgkmcnt(0)
	ds_write_b16 v181, v2
	v_add_u32_e32 v181, v182, v181
	ds_write_b16 v181, v2
	v_add_u32_e32 v181, v182, v181
	ds_write_b16 v181, v2
	v_add_u32_e32 v181, v182, v181
	ds_write_b16 v181, v2
	v_add_u32_e32 v181, v182, v181
	ds_write_b16 v181, v2
	v_add_u32_e32 v181, v182, v181
	ds_write_b16 v181, v2
	v_add_u32_e32 v181, v182, v181
	ds_write_b16 v181, v2
	v_add_u32_e32 v181, v182, v181
	ds_write_b16 v181, v2
	v_add_u32_e32 v181, v182, v181
	ds_write_b16 v181, v2
	v_add_u32_e32 v181, v182, v181
	ds_write_b16 v181, v2
	v_add_u32_e32 v181, v182, v181
	ds_write_b16 v181, v2
	v_add_u32_e32 v181, v182, v181
	ds_write_b16 v181, v2
	v_add_u32_e32 v181, v182, v181
	v_mul_f32_e32 v3, v232, v246
	v_cvt_pk_bf16_f32 v3, v3, s0
	ds_write_b16 v181, v3
	v_add_u32_e32 v181, v182, v181
	v_mul_f32_e32 v3, v233, v246
	v_cvt_pk_bf16_f32 v3, v3, s0
	ds_write_b16 v181, v3
	v_add_u32_e32 v181, v182, v181
	v_mul_f32_e32 v3, v234, v246
	v_cvt_pk_bf16_f32 v3, v3, s0
	ds_write_b16 v181, v3
	v_add_u32_e32 v181, v182, v181
	v_mul_f32_e32 v3, v235, v246
	v_cvt_pk_bf16_f32 v3, v3, s0
	ds_write_b16 v181, v3
.Ls4o_end:
	s_waitcnt lgkmcnt(0)
	v_readlane_b32 s2, v254, 53
	s_waitcnt lgkmcnt(0)
	s_barrier
	v_readlane_b32 s3, v254, 54
	s_and_b64 s[40:41], s[44:45], s[2:3]
	s_andn2_b64 vcc, exec, s[40:41]
	s_mov_b64 s[40:41], -1
	s_cbranch_vccz .LBB0_358
	v_cndmask_b32_e64 v2, 0, 1, s[44:45]
	s_nop 0
	v_readfirstlane_b32 s40, v2
	s_sub_i32 s46, s34, s40
	s_cmp_gt_i32 s46, 15
	s_cbranch_scc1 .LBB0_357
	s_and_b64 s[40:41], s[44:45], exec
	s_cselect_b32 s44, 7, 8
	s_lshl_b32 s45, s46, 6
	s_lshl_b32 s47, s44, 6
	s_branch .LBB0_345
